# v16 + next-tile stage-0 fragment ds_reads issued at K-loop exit (before the aligned SwiGLU epilogue, scratch regs renamed out of the fragment range)
# baseline (speedup 1.0000x reference)
; #define PG8_STAGE(bufoff, gbase, voff) do { _Pragma("unroll") for (int _i = 0; _i < 2; ++_i) \
;         __builtin_amdgcn_global_load_lds((const unsigned*)((const char*)(gbase) + (voff)[_i]), (LAS unsigned*)(lds + (bufoff) + ldsw + _i * 8192), 16, 0, 0); } while (0)
; #define PG8_WAIT_V(n) asm volatile("s_waitcnt vmcnt(" #n ")" ::: "memory")
; #define PG8_BAR __builtin_amdgcn_s_barrier()
; template <class Epi, class Sched>
; __device__ __forceinline__ void gemm_phase(LAS unsigned char* lds, const int lda, const int ldb, const int K, const Sched& S, const Epi& E) {
;     ...
;     for (int i = 0; i < 2; ++i) { int R, C; stage_rc(tid * 16 + i * 8192, R, C); const int Rb = (R & ~31) + perm32(R & 31);
;         voffA[i] = (unsigned)(R * lda + C) * 2u; voffB[i] = (unsigned)(Rb * ldb + C) * 2u; }
;     const size_t kstep = (size_t)(BK * 2);
;     const size_t hstepA = (size_t)HALF * lda * 2, hstepB = (size_t)HALF * ldb * 2;
;     const unsigned ldsw = (unsigned)wid * 1024u;
;     const int aoff = lds_byte(wr * 64 + fr, fq * 8), boff = lds_byte(wc * 32 + fr, fq * 8);
;     ...
;     Unit cur, nxt; int ui = 0;
;     if (!S.next(0, cur)) return;
;     f32x4 acc[2][2][4][2];
; #pragma unroll
;     for (int a = 0; a < 2; ++a)
; #pragma unroll
;         for (int b = 0; b < 2; ++b)
; #pragma unroll
;             for (int m = 0; m < 4; ++m)
; #pragma unroll
;                 for (int n = 0; n < 2; ++n) acc[a][b][m][n] = (f32x4){0.f, 0.f, 0.f, 0.f};
;     bf16x8 At[4][2], B0[2][2], B1[2][2];
;     float rsv[8];
; #pragma unroll
;     for (int i = 0; i < 8; ++i) rsv[i] = 0.f;
;     const char* cA = cur.A; const char* cB = cur.B;
;     PG8_STAGE(PG8_SB(0, 0), cB, voffB); PG8_STAGE(PG8_SB(0, 1), cB + hstepB, voffB); PG8_STAGE(PG8_SA(0, 0), cA, voffA); PG8_STAGE(PG8_SA(0, 1), cA + hstepA, voffA);
;     if (wr == 1) PG8_BAR;
;     PG8_WAIT_V(2); PG8_BAR;
;     PG8_STAGE(PG8_SB(1, 0), cB + kstep, voffB); PG8_STAGE(PG8_SA(1, 0), cA + kstep, voffA); PG8_STAGE(PG8_SB(1, 1), cB + hstepB + kstep, voffB);
;     PG8_WAIT_V(6); PG8_BAR;
.LBB0_235:
	s_lshl_b32 s8, s8, 5
	s_and_b32 s14, s8, 0x60
	s_mov_b64 s[8:9], 0x80
	s_add_i32 m0, s37, 0x18000
	v_lshl_add_u64 v[8:9], v[8:9], 0, s[8:9]
	s_lshl_b32 s11, s10, 13
	s_lshl_b32 s15, s14, 7
	s_waitcnt vmcnt(2)
	s_barrier
	global_load_lds_dwordx4 v[8:9], off
	v_lshl_add_u64 v[6:7], v[6:7], 0, s[8:9]
	s_add_i32 m0, s37, 0x1a000
	s_add_i32 s42, s37, 0x8000
	s_add_i32 s43, s37, 0xa000
	global_load_lds_dwordx4 v[6:7], off
	v_lshl_add_u64 v[2:3], v[2:3], 0, s[8:9]
	s_mov_b32 m0, s42
	s_add_u32 s12, s24, 0x40080
	global_load_lds_dwordx4 v[2:3], off
	v_lshl_add_u64 v[2:3], v[4:5], 0, s[8:9]
	s_mov_b32 m0, s43
	s_addc_u32 s13, s25, 0
	global_load_lds_dwordx4 v[2:3], off
	s_add_i32 m0, s37, 0x1c000
	v_lshl_add_u64 v[2:3], s[12:13], 0, v[200:201]
	global_load_lds_dwordx4 v[2:3], off
	v_lshl_add_u64 v[2:3], s[12:13], 0, v[196:197]
	s_add_i32 m0, s37, 0x1e000
	s_sext_i32_i16 s64, s0
	global_load_lds_dwordx4 v[2:3], off
	v_and_b32_e32 v2, 15, v194
	v_lshlrev_b32_e32 v3, 1, v13
	v_lshl_or_b32 v1, s10, 6, v2
	v_lshl_or_b32 v4, v2, 6, v3
	v_lshlrev_b32_e32 v2, 2, v2
	v_and_b32_e32 v5, 32, v2
	v_bitop3_b32 v4, v4, s11, v5 bitop3:0xde
	v_lshlrev_b32_e32 v5, 6, v194
	s_movk_i32 s0, 0x3c0
	v_and_or_b32 v3, v5, s0, v3
	v_lshlrev_b32_e32 v5, 2, v194
	s_lshl_b32 s0, s10, 8
	v_and_b32_e32 v5, 32, v5
	s_add_u32 s10, s84, s0
	v_bitop3_b32 v195, s15, v3, v5 bitop3:0xf6
	s_addc_u32 s11, s85, 0
	v_mov_b32_e32 v3, v201
	v_lshl_add_u64 v[204:205], s[10:11], 0, v[2:3]
	v_lshlrev_b32_e32 v2, 8, v194
	v_and_b32_e32 v2, 0x38000, v2
	v_lshlrev_b32_e32 v3, 11, v14
	v_or3_b32 v2, v11, v2, v3
	v_add_u32_e32 v206, v2, v12
	v_lshlrev_b32_e32 v2, 4, v10
	s_waitcnt vmcnt(6)
	s_cmpk_lt_u32 s1, 0x100
	v_and_b32_e32 v2, 0x78000, v2
	s_cselect_b64 s[10:11], -1, 0
	v_or3_b32 v2, v11, v2, v3
	s_add_i32 s50, 0, 0x10000
	s_add_i32 s51, 0, 0x14000
	s_ashr_i32 s44, s58, 31
	s_mov_b32 s45, s58
	v_or_b32_e32 v216, s14, v13
	v_mov_b32_e32 v207, v201
	v_add_u32_e32 v208, v2, v12
	v_mov_b32_e32 v209, v201
	v_mov_b64_e32 v[210:211], 0x2100
	v_mov_b64_e32 v[212:213], 0x20ff
	v_add_u32_e32 v217, s50, v195
	v_add_u32_e32 v218, s51, v195
	v_add_u32_e32 v219, 0, v4
	v_mov_b32_e32 v220, 0x358637bd
	s_mov_b32 s62, 0x800000
	s_movk_i32 s63, 0x1600
	v_mov_b32_e32 v221, v201
	v_mov_b32_e32 v222, v201
	v_mov_b32_e32 v223, v201
	v_mov_b32_e32 v224, v201
	v_mov_b32_e32 v225, v201
	v_mov_b32_e32 v226, v201
	v_mov_b32_e32 v227, v201
	v_mov_b32_e32 v228, v201
	s_mov_b64 s[18:19], s[24:25]
	s_mov_b64 s[16:17], s[22:23]
	s_barrier
	ds_read_b128 v[130:133], v217
	ds_read_b128 v[134:137], v217 offset:1024
	ds_read_b128 v[138:141], v217 offset:2048
	ds_read_b128 v[142:145], v217 offset:3072
	ds_read_b128 v[146:149], v218
	ds_read_b128 v[150:153], v218 offset:1024
	ds_read_b128 v[154:157], v218 offset:2048
	ds_read_b128 v[158:161], v218 offset:3072
	ds_read_b128 v[162:165], v219
	ds_read_b128 v[166:169], v219 offset:1024
	ds_read_b128 v[170:173], v219 offset:2048
	ds_read_b128 v[174:177], v219 offset:3072
	ds_read_b128 v[178:181], v219 offset:4096
	ds_read_b128 v[182:185], v219 offset:5120
	ds_read_b128 v[186:189], v219 offset:6144
	ds_read_b128 v[190:193], v219 offset:7168
	s_branch .LBB0_238

; #define PG8_STAGE(bufoff, gbase, voff) do { _Pragma("unroll") for (int _i = 0; _i < 2; ++_i) \
;         __builtin_amdgcn_global_load_lds((const unsigned*)((const char*)(gbase) + (voff)[_i]), (LAS unsigned*)(lds + (bufoff) + ldsw + _i * 8192), 16, 0, 0); } while (0)
; #define PG8_LDA(dst, b, h) do { _Pragma("unroll") for (int m = 0; m < 4; ++m) _Pragma("unroll") for (int k = 0; k < 2; ++k) dst[m][k] = *(const LAS bf16x8*)(lds + PG8_SA(b, h) + aoff + m * 2048 + k * 1024); } while (0)
; #define PG8_LDB(dst, b, h) do { _Pragma("unroll") for (int n = 0; n < 2; ++n) _Pragma("unroll") for (int k = 0; k < 2; ++k) dst[n][k] = *(const LAS bf16x8*)(lds + PG8_SB(b, h) + boff + n * 2048 + k * 1024); } while (0)
; #define PG8_MMA(ai, bj, At, Bt) do { __builtin_amdgcn_s_setprio(1); _Pragma("unroll") for (int m = 0; m < 4; ++m) _Pragma("unroll") for (int n = 0; n < 2; ++n) _Pragma("unroll") for (int k = 0; k < 2; ++k) \
;         acc[ai][bj][m][n] = __builtin_amdgcn_mfma_f32_16x16x32_bf16(Bt[n][k], At[m][k], acc[ai][bj][m][n], 0, 0, 0); __builtin_amdgcn_s_setprio(0); } while (0)
; #define PG8_WAIT_V(n) asm volatile("s_waitcnt vmcnt(" #n ")" ::: "memory")
; template <class Epi, class Sched>
; __device__ __forceinline__ void gemm_phase(LAS unsigned char* lds, const int lda, const int ldb, const int K, const Sched& S, const Epi& E) {
;     ...
;         const bool has_next = S.next(ui + 1, nxt);
;         const char* nA = has_next ? nxt.A : cA; const char* nB = has_next ? nxt.B : cB;
;         for (int t = 0; t < nt; t += 2) {
;             const bool last = (t == nt - 2);
;             const char* a1 = cA + (size_t)(t + 1) * kstep;
;             const char* a2 = last ? nA : cA + (size_t)(t + 2) * kstep; const char* b2 = last ? nB : cB + (size_t)(t + 2) * kstep;
;             const char* a3 = a2 + kstep; const char* b3 = b2 + kstep;
;             PG8_LDB(B0, 0, 0); PG8_LDB(B1, 0, 1); PG8_SCHED; PG8_LDA(At, 0, 0); PG8_STAGE(PG8_SA(1, 1), a1 + hstepA, voffA);
;             PG8_WAIT_V(8); PG8_WAIT_L(0); PG8_BAR; PG8_MMA(0, 0, At, B0); PG8_MMA(0, 1, At, B1); PG8_BAR; PG8_SCHED;
;             PG8_LDA(At, 0, 1); PG8_STAGE(PG8_SB(0, 0), b2, voffB); PG8_STAGE(PG8_SB(0, 1), b2 + hstepB, voffB); PG8_STAGE(PG8_SA(0, 0), a2, voffA);
;             PG8_WAIT_V(8); PG8_WAIT_L(0); PG8_BAR; PG8_MMA(1, 0, At, B0); PG8_MMA(1, 1, At, B1); PG8_BAR; PG8_SCHED;
.LBB0_240:
	s_lshl_b32 s20, s20, 8
	s_ashr_i32 s21, s20, 31
	s_add_u32 s22, s22, 0x40080
	s_addc_u32 s23, s23, 0
	s_add_u32 s13, s24, 0x100
	s_addc_u32 s15, s25, 0
	s_mov_b32 s65, -2
	v_lshl_add_u64 v[214:215], s[20:21], 2, v[204:205]
	v_add_u32_e32 v230, 0x80, v200
	v_add_u32_e32 v231, 0x80, v196
	v_add_u32_e32 v232, 0x80, v202
	v_add_u32_e32 v233, 0x80, v198
	s_add_u32 s21, s22, 0xfffc0080
	s_addc_u32 s24, s23, -1
	s_cmp_eq_u32 s65, 12
	s_cselect_b32 s29, s17, s24
	s_cselect_b32 s28, s16, s21
	s_cselect_b32 s31, s19, s15
	s_cselect_b32 s30, s18, s13
	s_add_i32 s72, s50, s3
	s_add_i32 m0, s37, 0xc000
	s_add_i32 s71, s37, 0xe000
	s_add_i32 s73, s72, 0x2000
	s_add_u32 s48, s30, 0x40000
	s_addc_u32 s49, s31, 0
	s_add_i32 s74, s51, s3
	s_add_i32 s75, s74, 0x2000
	s_add_i32 s76, 0, 0x18000
	s_add_i32 s77, 0, 0x1c000
	s_add_u32 s26, s28, 0x40000
	s_addc_u32 s27, s29, 0
	s_add_i32 s68, s76, s3
	s_add_i32 s21, s68, 0x2000
	s_add_u32 s24, s30, 0x40080
	s_addc_u32 s25, s31, 0
	s_add_i32 s70, s77, s3
	s_add_i32 s69, s70, 0x2000
	s_cmp_lg_u32 s65, 12
	global_load_lds_dwordx4 v206, s[22:23]
	s_mov_b32 m0, s71
	s_nop 0
	global_load_lds_dwordx4 v208, s[22:23]
	s_waitcnt vmcnt(8)
	s_waitcnt lgkmcnt(0)
	s_barrier
	s_setprio 1
	s_waitcnt lgkmcnt(0)
	v_mfma_f32_16x16x32_bf16 v[126:129], v[130:133], v[162:165], 0
	v_mfma_f32_16x16x32_bf16 v[118:121], v[138:141], v[162:165], 0
	v_mfma_f32_16x16x32_bf16 v[110:113], v[130:133], v[170:173], 0
	v_mfma_f32_16x16x32_bf16 v[102:105], v[138:141], v[170:173], 0
	v_mfma_f32_16x16x32_bf16 v[94:97], v[130:133], v[178:181], 0
	v_mfma_f32_16x16x32_bf16 v[86:89], v[138:141], v[178:181], 0
	v_mfma_f32_16x16x32_bf16 v[78:81], v[130:133], v[186:189], 0
	v_mfma_f32_16x16x32_bf16 v[70:73], v[138:141], v[186:189], 0
	v_mfma_f32_16x16x32_bf16 v[126:129], v[134:137], v[166:169], v[126:129]
	v_mfma_f32_16x16x32_bf16 v[118:121], v[142:145], v[166:169], v[118:121]
	v_mfma_f32_16x16x32_bf16 v[110:113], v[134:137], v[174:177], v[110:113]
	v_mfma_f32_16x16x32_bf16 v[102:105], v[142:145], v[174:177], v[102:105]
	v_mfma_f32_16x16x32_bf16 v[94:97], v[134:137], v[182:185], v[94:97]
	v_mfma_f32_16x16x32_bf16 v[86:89], v[142:145], v[182:185], v[86:89]
	v_mfma_f32_16x16x32_bf16 v[78:81], v[134:137], v[190:193], v[78:81]
	v_mfma_f32_16x16x32_bf16 v[70:73], v[142:145], v[190:193], v[70:73]
	s_setprio 0
	s_setprio 1
	v_mfma_f32_16x16x32_bf16 v[122:125], v[146:149], v[162:165], 0
	v_mfma_f32_16x16x32_bf16 v[114:117], v[154:157], v[162:165], 0
	v_mfma_f32_16x16x32_bf16 v[106:109], v[146:149], v[170:173], 0
	v_mfma_f32_16x16x32_bf16 v[98:101], v[154:157], v[170:173], 0
	v_mfma_f32_16x16x32_bf16 v[90:93], v[146:149], v[178:181], 0
	v_mfma_f32_16x16x32_bf16 v[82:85], v[154:157], v[178:181], 0
	v_mfma_f32_16x16x32_bf16 v[74:77], v[146:149], v[186:189], 0
	v_mfma_f32_16x16x32_bf16 v[66:69], v[154:157], v[186:189], 0
	v_mfma_f32_16x16x32_bf16 v[122:125], v[150:153], v[166:169], v[122:125]
	v_mfma_f32_16x16x32_bf16 v[114:117], v[158:161], v[166:169], v[114:117]
	v_mfma_f32_16x16x32_bf16 v[106:109], v[150:153], v[174:177], v[106:109]
	v_mfma_f32_16x16x32_bf16 v[98:101], v[158:161], v[174:177], v[98:101]
	v_mfma_f32_16x16x32_bf16 v[90:93], v[150:153], v[182:185], v[90:93]
	v_mfma_f32_16x16x32_bf16 v[82:85], v[158:161], v[182:185], v[82:85]
	v_mfma_f32_16x16x32_bf16 v[74:77], v[150:153], v[190:193], v[74:77]
	v_mfma_f32_16x16x32_bf16 v[66:69], v[158:161], v[190:193], v[66:69]
	s_setprio 0
	s_barrier
	s_mov_b32 m0, s72
	ds_read_b128 v[162:165], v219 offset:16384
	ds_read_b128 v[166:169], v219 offset:17408
	ds_read_b128 v[170:173], v219 offset:18432
	ds_read_b128 v[174:177], v219 offset:19456
	ds_read_b128 v[178:181], v219 offset:20480
	ds_read_b128 v[182:185], v219 offset:21504
	ds_read_b128 v[186:189], v219 offset:22528
	ds_read_b128 v[190:193], v219 offset:23552
	global_load_lds_dwordx4 v200, s[30:31]
	s_mov_b32 m0, s73
	s_nop 0
	global_load_lds_dwordx4 v196, s[30:31]
	s_mov_b32 m0, s74
	s_nop 0
	global_load_lds_dwordx4 v200, s[48:49]
	s_mov_b32 m0, s75
	s_nop 0
	global_load_lds_dwordx4 v196, s[48:49]
	s_mov_b32 m0, s37
	s_nop 0
	global_load_lds_dwordx4 v202, s[28:29]
	s_mov_b32 m0, s38
	s_nop 0
	global_load_lds_dwordx4 v198, s[28:29]
	s_waitcnt vmcnt(8)
	s_waitcnt lgkmcnt(0)
	s_barrier
	s_setprio 1
	s_waitcnt lgkmcnt(0)
	v_mfma_f32_16x16x32_bf16 v[62:65], v[130:133], v[162:165], 0
	v_mfma_f32_16x16x32_bf16 v[54:57], v[138:141], v[162:165], 0
	v_mfma_f32_16x16x32_bf16 v[46:49], v[130:133], v[170:173], 0
	v_mfma_f32_16x16x32_bf16 v[38:41], v[138:141], v[170:173], 0
	v_mfma_f32_16x16x32_bf16 v[30:33], v[130:133], v[178:181], 0
	v_mfma_f32_16x16x32_bf16 v[22:25], v[138:141], v[178:181], 0
	v_mfma_f32_16x16x32_bf16 v[14:17], v[130:133], v[186:189], 0
	v_mfma_f32_16x16x32_bf16 v[6:9], v[138:141], v[186:189], 0
	v_mfma_f32_16x16x32_bf16 v[62:65], v[134:137], v[166:169], v[62:65]
	v_mfma_f32_16x16x32_bf16 v[54:57], v[142:145], v[166:169], v[54:57]
	v_mfma_f32_16x16x32_bf16 v[46:49], v[134:137], v[174:177], v[46:49]
	v_mfma_f32_16x16x32_bf16 v[38:41], v[142:145], v[174:177], v[38:41]
	v_mfma_f32_16x16x32_bf16 v[30:33], v[134:137], v[182:185], v[30:33]
	v_mfma_f32_16x16x32_bf16 v[22:25], v[142:145], v[182:185], v[22:25]
	v_mfma_f32_16x16x32_bf16 v[14:17], v[134:137], v[190:193], v[14:17]
	v_mfma_f32_16x16x32_bf16 v[6:9], v[142:145], v[190:193], v[6:9]
	s_setprio 0
	s_setprio 1
	v_mfma_f32_16x16x32_bf16 v[58:61], v[146:149], v[162:165], 0
	v_mfma_f32_16x16x32_bf16 v[50:53], v[154:157], v[162:165], 0
	v_mfma_f32_16x16x32_bf16 v[42:45], v[146:149], v[170:173], 0
	v_mfma_f32_16x16x32_bf16 v[34:37], v[154:157], v[170:173], 0
	v_mfma_f32_16x16x32_bf16 v[26:29], v[146:149], v[178:181], 0
	v_mfma_f32_16x16x32_bf16 v[18:21], v[154:157], v[178:181], 0
	v_mfma_f32_16x16x32_bf16 v[10:13], v[146:149], v[186:189], 0
	v_mfma_f32_16x16x32_bf16 v[2:5], v[154:157], v[186:189], 0
	v_mfma_f32_16x16x32_bf16 v[58:61], v[150:153], v[166:169], v[58:61]
	v_mfma_f32_16x16x32_bf16 v[50:53], v[158:161], v[166:169], v[50:53]
	v_mfma_f32_16x16x32_bf16 v[42:45], v[150:153], v[174:177], v[42:45]
	v_mfma_f32_16x16x32_bf16 v[34:37], v[158:161], v[174:177], v[34:37]
	v_mfma_f32_16x16x32_bf16 v[26:29], v[150:153], v[182:185], v[26:29]
	v_mfma_f32_16x16x32_bf16 v[18:21], v[158:161], v[182:185], v[18:21]
	v_mfma_f32_16x16x32_bf16 v[10:13], v[150:153], v[190:193], v[10:13]
	v_mfma_f32_16x16x32_bf16 v[2:5], v[158:161], v[190:193], v[2:5]
	s_setprio 0
	s_barrier
	s_branch .Lpeel1_join

; __device__ __forceinline__ unsigned cvt_pk_bf16(float lo, float hi) { unsigned r; asm("v_cvt_pk_bf16_f32 %0, %1, %2" : "=v"(r) : "v"(lo), "v"(hi)); return r; }
; __device__ __forceinline__ float rcpf_(float x) { return __builtin_amdgcn_rcpf(x); }
; #define PG8_BAR __builtin_amdgcn_s_barrier()
; template <class Epi, class Sched>
; __device__ __forceinline__ void gemm_phase(LAS unsigned char* lds, const int lda, const int ldb, const int K, const Sched& S, const Epi& E) {
;     ...
;         if (wr == 0) PG8_BAR;
;         const bool keep = E(acc, cur, wr, wc, fr, fq, rsv);
;     __device__ __forceinline__ bool operator()(AccT& acc, const pg8::Unit& u, int wr, int wc, int fr, int fq, const float (&rsv)[8]) const {
;         const int row0 = u.pm * 256 + wr * 64 + fr, col0 = u.pn * 128 + wc * 32 + 8 * fq;
; #pragma unroll
;         for (int ai = 0; ai < 2; ++ai)
; #pragma unroll
;             for (int m = 0; m < 4; ++m) {
;                 const int row = row0 + ai * 128 + m * 16; const float r = rsqrtf(rsv[ai * 4 + m] * (1.f / 1024.f) + EPS);
;                 typedef float f32x2 __attribute__((ext_vector_type(2)));
;                 const float rn = r * -1.4426950408889634f, r2 = r * r;
;                 u32x4 w;
; #pragma unroll
;                 for (int n = 0; n < 2; ++n) {
;                     const f32x4 gv = acc[ai][0][m][n], uv = acc[ai][1][m][n];
; #pragma unroll
;                     for (int p = 0; p < 2; ++p) {
;                         const f32x2 g2 = {gv[2 * p], gv[2 * p + 1]}, u2 = {uv[2 * p], uv[2 * p + 1]};
;                         const f32x2 x2 = g2 * rn; f32x2 e2; e2.x = __builtin_amdgcn_exp2f(x2.x); e2.y = __builtin_amdgcn_exp2f(x2.y);
;                         const f32x2 d2 = e2 + 1.0f; f32x2 c2; c2.x = rcpf_(d2.x); c2.y = rcpf_(d2.y);
;                         const f32x2 h2 = (g2 * u2) * (c2 * r2);
;                         w[2 * n + p] = cvt_pk_bf16(h2.x, h2.y); } }
;                 *(u32x4*)(H + (size_t)row * FF + col0) = w;
.LBB0_244:
	ds_read_b128 v[130:133], v217
	ds_read_b128 v[134:137], v217 offset:1024
	ds_read_b128 v[138:141], v217 offset:2048
	ds_read_b128 v[142:145], v217 offset:3072
	ds_read_b128 v[146:149], v218
	ds_read_b128 v[150:153], v218 offset:1024
	ds_read_b128 v[154:157], v218 offset:2048
	ds_read_b128 v[158:161], v218 offset:3072
	ds_read_b128 v[162:165], v219
	ds_read_b128 v[166:169], v219 offset:1024
	ds_read_b128 v[170:173], v219 offset:2048
	ds_read_b128 v[174:177], v219 offset:3072
	ds_read_b128 v[178:181], v219 offset:4096
	ds_read_b128 v[182:185], v219 offset:5120
	ds_read_b128 v[186:189], v219 offset:6144
	ds_read_b128 v[190:193], v219 offset:7168
	s_and_b64 vcc, exec, s[10:11]
	s_cbranch_vccz .LBB0_246
	s_barrier
.LBB0_246:
	s_waitcnt vmcnt(0)
	v_fmamk_f32 v230, v228, 0x3a800000, v220
	v_mul_f32_e32 v231, 0x4b800000, v230
	v_cmp_gt_f32_e32 vcc, s62, v230
	v_pk_mul_f32 v[122:123], v[126:127], v[122:123]
	v_pk_mul_f32 v[124:125], v[128:129], v[124:125]
	v_cndmask_b32_e32 v230, v230, v231, vcc
	v_rsq_f32_e32 v231, v230
	v_pk_mul_f32 v[114:115], v[118:119], v[114:115]
	v_pk_mul_f32 v[116:117], v[120:121], v[116:117]
	v_lshl_or_b32 v236, s64, 7, v216
	v_mul_f32_e32 v232, 0x45800000, v231
	v_cndmask_b32_e32 v231, v231, v232, vcc
	v_mul_f32_e32 v232, 0xbfb8aa3b, v231
	v_pk_mul_f32 v[234:235], v[126:127], v[232:233] op_sel_hi:[1,0]
	v_pk_mul_f32 v[126:127], v[128:129], v[232:233] op_sel_hi:[1,0]
	v_exp_f32_e32 v234, v234
	v_exp_f32_e32 v235, v235
	v_exp_f32_e32 v126, v126
	v_exp_f32_e32 v127, v127
	v_mul_f32_e32 v238, v231, v231
	v_pk_add_f32 v[234:235], v[234:235], 1.0 op_sel_hi:[1,0]
	v_add_u32_e32 v230, s20, v1
	v_rcp_f32_e32 v234, v234
	v_rcp_f32_e32 v235, v235
	v_pk_add_f32 v[126:127], v[126:127], 1.0 op_sel_hi:[1,0]
	v_ashrrev_i32_e32 v237, 31, v236
	v_rcp_f32_e32 v126, v126
	v_rcp_f32_e32 v127, v127
	v_pk_mul_f32 v[128:129], v[238:239], v[234:235] op_sel_hi:[0,1]
	v_pk_mul_f32 v[122:123], v[122:123], v[128:129]
	v_pk_mul_f32 v[128:129], v[118:119], v[232:233] op_sel_hi:[1,0]
	v_pk_mul_f32 v[126:127], v[238:239], v[126:127] op_sel_hi:[0,1]
	v_exp_f32_e32 v128, v128
	v_exp_f32_e32 v129, v129
	v_pk_mul_f32 v[124:125], v[124:125], v[126:127]
	v_pk_mul_f32 v[126:127], v[120:121], v[232:233] op_sel_hi:[1,0]
	v_cvt_pk_bf16_f32 v122, v122, v123
	v_cvt_pk_bf16_f32 v123, v124, v125
	v_pk_add_f32 v[124:125], v[128:129], 1.0 op_sel_hi:[1,0]
	v_exp_f32_e32 v126, v126
	v_exp_f32_e32 v127, v127
	v_rcp_f32_e32 v124, v124
	v_rcp_f32_e32 v125, v125
	v_pk_mul_f32 v[106:107], v[110:111], v[106:107]
	v_pk_add_f32 v[118:119], v[126:127], 1.0 op_sel_hi:[1,0]
	v_pk_mul_f32 v[108:109], v[112:113], v[108:109]
	v_rcp_f32_e32 v118, v118
	v_rcp_f32_e32 v119, v119
	v_pk_mul_f32 v[120:121], v[238:239], v[124:125] op_sel_hi:[0,1]
	v_pk_mul_f32 v[114:115], v[114:115], v[120:121]
	v_pk_mul_f32 v[98:99], v[102:103], v[98:99]
	v_cvt_pk_bf16_f32 v124, v114, v115
	v_pk_mul_f32 v[114:115], v[238:239], v[118:119] op_sel_hi:[0,1]
	v_pk_mul_f32 v[114:115], v[116:117], v[114:115]
	v_fmamk_f32 v116, v227, 0x3a800000, v220
	v_mul_f32_e32 v117, 0x4b800000, v116
	v_cmp_gt_f32_e32 vcc, s62, v116
	v_cvt_pk_bf16_f32 v125, v114, v115
	v_mov_b64_e32 v[114:115], s[46:47]
	v_mad_i64_i32 v[118:119], s[20:21], v230, s63, v[114:115]
	v_cndmask_b32_e32 v116, v116, v117, vcc
	v_rsq_f32_e32 v120, v116
	v_lshlrev_b64 v[116:117], 1, v[236:237]
	v_lshl_add_u64 v[118:119], v[118:119], 0, v[116:117]
	global_store_dwordx4 v[118:119], v[122:125], off
	v_mul_f32_e32 v121, 0x45800000, v120
	v_cndmask_b32_e32 v121, v120, v121, vcc
	v_mul_f32_e32 v120, 0xbfb8aa3b, v121
	v_pk_mul_f32 v[126:127], v[110:111], v[120:121] op_sel_hi:[1,0]
	v_pk_mul_f32 v[110:111], v[112:113], v[120:121] op_sel_hi:[1,0]
	v_exp_f32_e32 v126, v126
	v_exp_f32_e32 v127, v127
	v_exp_f32_e32 v110, v110
	v_exp_f32_e32 v111, v111
	v_mul_f32_e32 v118, v121, v121
	v_pk_add_f32 v[122:123], v[126:127], 1.0 op_sel_hi:[1,0]
	v_pk_mul_f32 v[100:101], v[104:105], v[100:101]
	v_rcp_f32_e32 v122, v122
	v_rcp_f32_e32 v123, v123
	v_pk_add_f32 v[110:111], v[110:111], 1.0 op_sel_hi:[1,0]
	v_pk_mul_f32 v[90:91], v[94:95], v[90:91]
	v_rcp_f32_e32 v110, v110
	v_rcp_f32_e32 v111, v111
	v_pk_mul_f32 v[112:113], v[118:119], v[122:123] op_sel_hi:[0,1]
	v_pk_mul_f32 v[106:107], v[106:107], v[112:113]
	v_pk_mul_f32 v[112:113], v[102:103], v[120:121] op_sel_hi:[1,0]
	v_pk_mul_f32 v[110:111], v[118:119], v[110:111] op_sel_hi:[0,1]
	v_exp_f32_e32 v112, v112
	v_exp_f32_e32 v113, v113
	v_pk_mul_f32 v[108:109], v[108:109], v[110:111]
	v_pk_mul_f32 v[110:111], v[104:105], v[120:121] op_sel_hi:[1,0]
	v_cvt_pk_bf16_f32 v106, v106, v107
	v_cvt_pk_bf16_f32 v107, v108, v109
	v_pk_add_f32 v[108:109], v[112:113], 1.0 op_sel_hi:[1,0]
	v_exp_f32_e32 v110, v110
	v_exp_f32_e32 v111, v111
	v_rcp_f32_e32 v108, v108
	v_rcp_f32_e32 v109, v109
	v_pk_mul_f32 v[92:93], v[96:97], v[92:93]
	v_pk_add_f32 v[102:103], v[110:111], 1.0 op_sel_hi:[1,0]
	v_pk_mul_f32 v[82:83], v[86:87], v[82:83]
	v_rcp_f32_e32 v102, v102
	v_rcp_f32_e32 v103, v103
	v_pk_mul_f32 v[104:105], v[118:119], v[108:109] op_sel_hi:[0,1]
	v_pk_mul_f32 v[98:99], v[98:99], v[104:105]
	v_pk_mul_f32 v[84:85], v[88:89], v[84:85]
	v_cvt_pk_bf16_f32 v108, v98, v99
	v_pk_mul_f32 v[98:99], v[118:119], v[102:103] op_sel_hi:[0,1]
	v_pk_mul_f32 v[98:99], v[100:101], v[98:99]
	v_pk_mul_f32 v[74:75], v[78:79], v[74:75]
	v_cvt_pk_bf16_f32 v109, v98, v99
	v_fmamk_f32 v98, v226, 0x3a800000, v220
	v_mul_f32_e32 v99, 0x4b800000, v98
	v_cmp_gt_f32_e32 vcc, s62, v98
	v_pk_mul_f32 v[76:77], v[80:81], v[76:77]
	v_pk_mul_f32 v[66:67], v[70:71], v[66:67]
	v_cndmask_b32_e32 v98, v98, v99, vcc
	v_rsq_f32_e32 v100, v98
	v_or_b32_e32 v98, 16, v230
; __device__ __forceinline__ unsigned cvt_pk_bf16(float lo, float hi) { unsigned r; asm("v_cvt_pk_bf16_f32 %0, %1, %2" : "=v"(r) : "v"(lo), "v"(hi)); return r; }
; __device__ __forceinline__ float rcpf_(float x) { return __builtin_amdgcn_rcpf(x); }
;     __device__ __forceinline__ bool operator()(AccT& acc, const pg8::Unit& u, int wr, int wc, int fr, int fq, const float (&rsv)[8]) const {
;     ...
;         for (int ai = 0; ai < 2; ++ai)
; #pragma unroll
;             for (int m = 0; m < 4; ++m) {
;                 const int row = row0 + ai * 128 + m * 16; const float r = rsqrtf(rsv[ai * 4 + m] * (1.f / 1024.f) + EPS);
;                 typedef float f32x2 __attribute__((ext_vector_type(2)));
;                 const float rn = r * -1.4426950408889634f, r2 = r * r;
;                 u32x4 w;
; #pragma unroll
;                 for (int n = 0; n < 2; ++n) {
;                     const f32x4 gv = acc[ai][0][m][n], uv = acc[ai][1][m][n];
; #pragma unroll
;                     for (int p = 0; p < 2; ++p) {
;                         const f32x2 g2 = {gv[2 * p], gv[2 * p + 1]}, u2 = {uv[2 * p], uv[2 * p + 1]};
;                         const f32x2 x2 = g2 * rn; f32x2 e2; e2.x = __builtin_amdgcn_exp2f(x2.x); e2.y = __builtin_amdgcn_exp2f(x2.y);
;                         const f32x2 d2 = e2 + 1.0f; f32x2 c2; c2.x = rcpf_(d2.x); c2.y = rcpf_(d2.y);
;                         const f32x2 h2 = (g2 * u2) * (c2 * r2);
;                         w[2 * n + p] = cvt_pk_bf16(h2.x, h2.y); } }
;                 *(u32x4*)(H + (size_t)row * FF + col0) = w;
	v_mad_i64_i32 v[98:99], s[20:21], v98, s63, v[114:115]
	v_mul_f32_e32 v101, 0x45800000, v100
	v_cndmask_b32_e32 v101, v100, v101, vcc
	v_mul_f32_e32 v100, 0xbfb8aa3b, v101
	v_pk_mul_f32 v[102:103], v[94:95], v[100:101] op_sel_hi:[1,0]
	v_pk_mul_f32 v[94:95], v[96:97], v[100:101] op_sel_hi:[1,0]
	v_exp_f32_e32 v102, v102
	v_exp_f32_e32 v103, v103
	v_exp_f32_e32 v94, v94
	v_exp_f32_e32 v95, v95
	v_lshl_add_u64 v[98:99], v[98:99], 0, v[116:117]
	v_pk_add_f32 v[102:103], v[102:103], 1.0 op_sel_hi:[1,0]
	global_store_dwordx4 v[98:99], v[106:109], off
	v_rcp_f32_e32 v102, v102
	v_rcp_f32_e32 v103, v103
	v_pk_add_f32 v[94:95], v[94:95], 1.0 op_sel_hi:[1,0]
	v_mul_f32_e32 v98, v101, v101
	v_rcp_f32_e32 v94, v94
	v_rcp_f32_e32 v95, v95
	v_pk_mul_f32 v[96:97], v[98:99], v[102:103] op_sel_hi:[0,1]
	v_pk_mul_f32 v[90:91], v[90:91], v[96:97]
	v_pk_mul_f32 v[96:97], v[86:87], v[100:101] op_sel_hi:[1,0]
	v_pk_mul_f32 v[94:95], v[98:99], v[94:95] op_sel_hi:[0,1]
	v_exp_f32_e32 v96, v96
	v_exp_f32_e32 v97, v97
	v_pk_mul_f32 v[92:93], v[92:93], v[94:95]
	v_pk_mul_f32 v[94:95], v[88:89], v[100:101] op_sel_hi:[1,0]
	v_cvt_pk_bf16_f32 v90, v90, v91
	v_cvt_pk_bf16_f32 v91, v92, v93
	v_pk_add_f32 v[92:93], v[96:97], 1.0 op_sel_hi:[1,0]
	v_exp_f32_e32 v94, v94
	v_exp_f32_e32 v95, v95
	v_rcp_f32_e32 v92, v92
	v_rcp_f32_e32 v93, v93
	v_pk_mul_f32 v[68:69], v[72:73], v[68:69]
	v_pk_add_f32 v[86:87], v[94:95], 1.0 op_sel_hi:[1,0]
	v_pk_mul_f32 v[58:59], v[62:63], v[58:59]
	v_rcp_f32_e32 v86, v86
	v_rcp_f32_e32 v87, v87
	v_pk_mul_f32 v[88:89], v[98:99], v[92:93] op_sel_hi:[0,1]
	v_pk_mul_f32 v[82:83], v[82:83], v[88:89]
	v_pk_mul_f32 v[60:61], v[64:65], v[60:61]
	v_cvt_pk_bf16_f32 v92, v82, v83
	v_pk_mul_f32 v[82:83], v[98:99], v[86:87] op_sel_hi:[0,1]
	v_pk_mul_f32 v[82:83], v[84:85], v[82:83]
	v_pk_mul_f32 v[50:51], v[54:55], v[50:51]
	v_cvt_pk_bf16_f32 v93, v82, v83
	v_fmamk_f32 v82, v225, 0x3a800000, v220
	v_mul_f32_e32 v83, 0x4b800000, v82
	v_cmp_gt_f32_e32 vcc, s62, v82
	v_pk_mul_f32 v[52:53], v[56:57], v[52:53]
	v_pk_mul_f32 v[42:43], v[46:47], v[42:43]
	v_cndmask_b32_e32 v82, v82, v83, vcc
	v_rsq_f32_e32 v84, v82
	v_or_b32_e32 v82, 32, v230
	v_mad_i64_i32 v[82:83], s[20:21], v82, s63, v[114:115]
	v_mul_f32_e32 v85, 0x45800000, v84
	v_cndmask_b32_e32 v85, v84, v85, vcc
	v_mul_f32_e32 v84, 0xbfb8aa3b, v85
	v_pk_mul_f32 v[86:87], v[78:79], v[84:85] op_sel_hi:[1,0]
	v_pk_mul_f32 v[78:79], v[80:81], v[84:85] op_sel_hi:[1,0]
	v_exp_f32_e32 v86, v86
	v_exp_f32_e32 v87, v87
	v_exp_f32_e32 v78, v78
	v_exp_f32_e32 v79, v79
	v_lshl_add_u64 v[82:83], v[82:83], 0, v[116:117]
	v_pk_add_f32 v[86:87], v[86:87], 1.0 op_sel_hi:[1,0]
	global_store_dwordx4 v[82:83], v[90:93], off
	v_rcp_f32_e32 v86, v86
	v_rcp_f32_e32 v87, v87
	v_pk_add_f32 v[78:79], v[78:79], 1.0 op_sel_hi:[1,0]
	v_mul_f32_e32 v82, v85, v85
	v_rcp_f32_e32 v78, v78
	v_rcp_f32_e32 v79, v79
	v_pk_mul_f32 v[80:81], v[82:83], v[86:87] op_sel_hi:[0,1]
	v_pk_mul_f32 v[74:75], v[74:75], v[80:81]
	v_pk_mul_f32 v[80:81], v[70:71], v[84:85] op_sel_hi:[1,0]
	v_pk_mul_f32 v[78:79], v[82:83], v[78:79] op_sel_hi:[0,1]
	v_exp_f32_e32 v80, v80
	v_exp_f32_e32 v81, v81
	v_pk_mul_f32 v[76:77], v[76:77], v[78:79]
	v_pk_mul_f32 v[78:79], v[72:73], v[84:85] op_sel_hi:[1,0]
	v_cvt_pk_bf16_f32 v74, v74, v75
	v_cvt_pk_bf16_f32 v75, v76, v77
	v_pk_add_f32 v[76:77], v[80:81], 1.0 op_sel_hi:[1,0]
	v_exp_f32_e32 v78, v78
	v_exp_f32_e32 v79, v79
	v_rcp_f32_e32 v76, v76
	v_rcp_f32_e32 v77, v77
	v_pk_mul_f32 v[44:45], v[48:49], v[44:45]
	v_pk_add_f32 v[70:71], v[78:79], 1.0 op_sel_hi:[1,0]
	v_pk_mul_f32 v[34:35], v[38:39], v[34:35]
	v_rcp_f32_e32 v70, v70
	v_rcp_f32_e32 v71, v71
	v_pk_mul_f32 v[72:73], v[82:83], v[76:77] op_sel_hi:[0,1]
	v_pk_mul_f32 v[66:67], v[66:67], v[72:73]
	v_pk_mul_f32 v[36:37], v[40:41], v[36:37]
	v_cvt_pk_bf16_f32 v76, v66, v67
	v_pk_mul_f32 v[66:67], v[82:83], v[70:71] op_sel_hi:[0,1]
	v_pk_mul_f32 v[66:67], v[68:69], v[66:67]
	v_pk_mul_f32 v[26:27], v[30:31], v[26:27]
	v_cvt_pk_bf16_f32 v77, v66, v67
	v_fmamk_f32 v67, v224, 0x3a800000, v220
	v_mul_f32_e32 v68, 0x4b800000, v67
	v_cmp_gt_f32_e32 vcc, s62, v67
	v_or_b32_e32 v66, 48, v230
	v_pk_mul_f32 v[28:29], v[32:33], v[28:29]
	v_cndmask_b32_e32 v67, v67, v68, vcc
	v_rsq_f32_e32 v68, v67
	v_mad_i64_i32 v[66:67], s[20:21], v66, s63, v[114:115]
	v_lshl_add_u64 v[66:67], v[66:67], 0, v[116:117]
	v_mul_f32_e32 v69, 0x45800000, v68
	v_cndmask_b32_e32 v69, v68, v69, vcc
	v_mul_f32_e32 v68, 0xbfb8aa3b, v69
	v_pk_mul_f32 v[70:71], v[62:63], v[68:69] op_sel_hi:[1,0]
	v_pk_mul_f32 v[62:63], v[64:65], v[68:69] op_sel_hi:[1,0]
	v_exp_f32_e32 v70, v70
	v_exp_f32_e32 v71, v71
	v_exp_f32_e32 v62, v62
	v_exp_f32_e32 v63, v63
	global_store_dwordx4 v[66:67], v[74:77], off
	v_pk_add_f32 v[70:71], v[70:71], 1.0 op_sel_hi:[1,0]
	v_add_u32_e32 v67, 0x80, v230
	v_rcp_f32_e32 v70, v70
	v_rcp_f32_e32 v71, v71
	v_pk_add_f32 v[62:63], v[62:63], 1.0 op_sel_hi:[1,0]
	v_mul_f32_e32 v66, v69, v69
	v_rcp_f32_e32 v62, v62
	v_rcp_f32_e32 v63, v63
	v_pk_mul_f32 v[64:65], v[66:67], v[70:71] op_sel_hi:[0,1]
	v_pk_mul_f32 v[58:59], v[64:65], v[58:59]
	v_pk_mul_f32 v[64:65], v[54:55], v[68:69] op_sel_hi:[1,0]
	v_pk_mul_f32 v[62:63], v[66:67], v[62:63] op_sel_hi:[0,1]
	v_exp_f32_e32 v64, v64
	v_exp_f32_e32 v65, v65
	v_pk_mul_f32 v[60:61], v[62:63], v[60:61]
	v_pk_mul_f32 v[62:63], v[56:57], v[68:69] op_sel_hi:[1,0]
	v_cvt_pk_bf16_f32 v58, v58, v59
	v_cvt_pk_bf16_f32 v59, v60, v61
	v_pk_add_f32 v[60:61], v[64:65], 1.0 op_sel_hi:[1,0]
	v_exp_f32_e32 v62, v62
	v_exp_f32_e32 v63, v63
	v_rcp_f32_e32 v60, v60
	v_rcp_f32_e32 v61, v61
	v_pk_mul_f32 v[18:19], v[22:23], v[18:19]
	v_pk_add_f32 v[54:55], v[62:63], 1.0 op_sel_hi:[1,0]
; __device__ __forceinline__ unsigned cvt_pk_bf16(float lo, float hi) { unsigned r; asm("v_cvt_pk_bf16_f32 %0, %1, %2" : "=v"(r) : "v"(lo), "v"(hi)); return r; }
; __device__ __forceinline__ float rcpf_(float x) { return __builtin_amdgcn_rcpf(x); }
; #define PG8_WAIT_V(n) asm volatile("s_waitcnt vmcnt(" #n ")" ::: "memory")
; template <class Epi, class Sched>
; __device__ __forceinline__ void gemm_phase(LAS unsigned char* lds, const int lda, const int ldb, const int K, const Sched& S, const Epi& E) {
;     ...
;         if (wr == 0) PG8_BAR;
;         const bool keep = E(acc, cur, wr, wc, fr, fq, rsv);
;         if (!has_next) break;
;         if (!keep) {
; #pragma unroll
;             for (int a = 0; a < 2; ++a)
; #pragma unroll
;                 for (int b = 0; b < 2; ++b)
; #pragma unroll
;                     for (int m = 0; m < 4; ++m)
; #pragma unroll
;                         for (int n = 0; n < 2; ++n) acc[a][b][m][n] = (f32x4){0.f, 0.f, 0.f, 0.f};
;         }
;         cur = nxt; cA = nA; cB = nB; ++ui;
;         if (wr == 1) PG8_BAR;
;     }
;     PG8_WAIT_V(0);
;     PG8_BAR;
;     __device__ __forceinline__ bool operator()(AccT& acc, const pg8::Unit& u, int wr, int wc, int fr, int fq, const float (&rsv)[8]) const {
;     ...
;         for (int ai = 0; ai < 2; ++ai)
; #pragma unroll
;             for (int m = 0; m < 4; ++m) {
;                 const int row = row0 + ai * 128 + m * 16; const float r = rsqrtf(rsv[ai * 4 + m] * (1.f / 1024.f) + EPS);
;                 typedef float f32x2 __attribute__((ext_vector_type(2)));
;                 const float rn = r * -1.4426950408889634f, r2 = r * r;
;                 u32x4 w;
; #pragma unroll
;                 for (int n = 0; n < 2; ++n) {
;                     const f32x4 gv = acc[ai][0][m][n], uv = acc[ai][1][m][n];
; #pragma unroll
;                     for (int p = 0; p < 2; ++p) {
;                         const f32x2 g2 = {gv[2 * p], gv[2 * p + 1]}, u2 = {uv[2 * p], uv[2 * p + 1]};
;                         const f32x2 x2 = g2 * rn; f32x2 e2; e2.x = __builtin_amdgcn_exp2f(x2.x); e2.y = __builtin_amdgcn_exp2f(x2.y);
;                         const f32x2 d2 = e2 + 1.0f; f32x2 c2; c2.x = rcpf_(d2.x); c2.y = rcpf_(d2.y);
;                         const f32x2 h2 = (g2 * u2) * (c2 * r2);
;                         w[2 * n + p] = cvt_pk_bf16(h2.x, h2.y); } }
;                 *(u32x4*)(H + (size_t)row * FF + col0) = w;
	v_pk_mul_f32 v[20:21], v[24:25], v[20:21]
	v_rcp_f32_e32 v54, v54
	v_rcp_f32_e32 v55, v55
	v_pk_mul_f32 v[56:57], v[66:67], v[60:61] op_sel_hi:[0,1]
	v_pk_mul_f32 v[50:51], v[56:57], v[50:51]
	v_pk_mul_f32 v[10:11], v[14:15], v[10:11]
	v_cvt_pk_bf16_f32 v60, v50, v51
	v_pk_mul_f32 v[50:51], v[66:67], v[54:55] op_sel_hi:[0,1]
	v_pk_mul_f32 v[50:51], v[50:51], v[52:53]
	v_fmamk_f32 v52, v223, 0x3a800000, v220
	v_mul_f32_e32 v53, 0x4b800000, v52
	v_cmp_gt_f32_e32 vcc, s62, v52
	v_cvt_pk_bf16_f32 v61, v50, v51
	v_mad_i64_i32 v[50:51], s[20:21], v67, s63, v[114:115]
	s_nop 0
	v_cndmask_b32_e32 v52, v52, v53, vcc
	v_rsq_f32_e32 v52, v52
	v_lshl_add_u64 v[50:51], v[50:51], 0, v[116:117]
	global_store_dwordx4 v[50:51], v[58:61], off
	v_pk_mul_f32 v[12:13], v[16:17], v[12:13]
	v_mul_f32_e32 v53, 0x45800000, v52
	v_cndmask_b32_e32 v53, v52, v53, vcc
	v_mul_f32_e32 v52, 0xbfb8aa3b, v53
	v_pk_mul_f32 v[54:55], v[52:53], v[46:47] op_sel_hi:[0,1]
	v_exp_f32_e32 v54, v54
	v_exp_f32_e32 v55, v55
	v_pk_mul_f32 v[46:47], v[52:53], v[48:49] op_sel_hi:[0,1]
	v_exp_f32_e32 v46, v46
	v_exp_f32_e32 v47, v47
	v_pk_add_f32 v[54:55], v[54:55], 1.0 op_sel_hi:[1,0]
	v_mul_f32_e32 v50, v53, v53
	v_rcp_f32_e32 v54, v54
	v_rcp_f32_e32 v55, v55
	v_pk_add_f32 v[46:47], v[46:47], 1.0 op_sel_hi:[1,0]
	v_pk_mul_f32 v[2:3], v[6:7], v[2:3]
	v_rcp_f32_e32 v46, v46
	v_rcp_f32_e32 v47, v47
	v_pk_mul_f32 v[48:49], v[50:51], v[54:55] op_sel_hi:[0,1]
	v_pk_mul_f32 v[42:43], v[48:49], v[42:43]
	v_pk_mul_f32 v[48:49], v[52:53], v[38:39] op_sel_hi:[0,1]
	v_exp_f32_e32 v48, v48
	v_exp_f32_e32 v49, v49
	v_pk_mul_f32 v[46:47], v[50:51], v[46:47] op_sel_hi:[0,1]
	v_pk_mul_f32 v[44:45], v[46:47], v[44:45]
	v_pk_mul_f32 v[46:47], v[52:53], v[40:41] op_sel_hi:[0,1]
	v_exp_f32_e32 v46, v46
	v_exp_f32_e32 v47, v47
	v_cvt_pk_bf16_f32 v42, v42, v43
	v_cvt_pk_bf16_f32 v43, v44, v45
	v_pk_add_f32 v[44:45], v[48:49], 1.0 op_sel_hi:[1,0]
	v_pk_add_f32 v[38:39], v[46:47], 1.0 op_sel_hi:[1,0]
	v_rcp_f32_e32 v44, v44
	v_rcp_f32_e32 v45, v45
	v_rcp_f32_e32 v38, v38
	v_rcp_f32_e32 v39, v39
	v_pk_mul_f32 v[4:5], v[8:9], v[4:5]
	v_pk_mul_f32 v[40:41], v[50:51], v[44:45] op_sel_hi:[0,1]
	v_pk_mul_f32 v[34:35], v[40:41], v[34:35]
	s_nop 0
	v_cvt_pk_bf16_f32 v44, v34, v35
	v_pk_mul_f32 v[34:35], v[50:51], v[38:39] op_sel_hi:[0,1]
	v_pk_mul_f32 v[34:35], v[34:35], v[36:37]
	s_nop 0
	v_cvt_pk_bf16_f32 v45, v34, v35
	v_fmamk_f32 v34, v222, 0x3a800000, v220
	v_mul_f32_e32 v35, 0x4b800000, v34
	v_cmp_gt_f32_e32 vcc, s62, v34
	s_nop 1
	v_cndmask_b32_e32 v34, v34, v35, vcc
	v_rsq_f32_e32 v36, v34
	v_add_u32_e32 v34, 0x90, v230
	v_mad_i64_i32 v[34:35], s[20:21], v34, s63, v[114:115]
	v_mul_f32_e32 v37, 0x45800000, v36
	v_cndmask_b32_e32 v37, v36, v37, vcc
	v_mul_f32_e32 v36, 0xbfb8aa3b, v37
	v_pk_mul_f32 v[38:39], v[36:37], v[30:31] op_sel_hi:[0,1]
	v_exp_f32_e32 v38, v38
	v_exp_f32_e32 v39, v39
	v_pk_mul_f32 v[30:31], v[36:37], v[32:33] op_sel_hi:[0,1]
	v_exp_f32_e32 v30, v30
	v_exp_f32_e32 v31, v31
	v_pk_add_f32 v[38:39], v[38:39], 1.0 op_sel_hi:[1,0]
	v_lshl_add_u64 v[34:35], v[34:35], 0, v[116:117]
	v_rcp_f32_e32 v38, v38
	v_rcp_f32_e32 v39, v39
	v_pk_add_f32 v[30:31], v[30:31], 1.0 op_sel_hi:[1,0]
	global_store_dwordx4 v[34:35], v[42:45], off
	v_rcp_f32_e32 v30, v30
	v_rcp_f32_e32 v31, v31
	v_mul_f32_e32 v34, v37, v37
	v_pk_mul_f32 v[32:33], v[34:35], v[38:39] op_sel_hi:[0,1]
	v_pk_mul_f32 v[26:27], v[32:33], v[26:27]
	v_pk_mul_f32 v[32:33], v[36:37], v[22:23] op_sel_hi:[0,1]
	v_exp_f32_e32 v32, v32
	v_exp_f32_e32 v33, v33
	v_pk_mul_f32 v[30:31], v[34:35], v[30:31] op_sel_hi:[0,1]
	v_pk_mul_f32 v[28:29], v[30:31], v[28:29]
	v_pk_mul_f32 v[30:31], v[36:37], v[24:25] op_sel_hi:[0,1]
	v_exp_f32_e32 v30, v30
	v_exp_f32_e32 v31, v31
	v_cvt_pk_bf16_f32 v26, v26, v27
	v_cvt_pk_bf16_f32 v27, v28, v29
	v_pk_add_f32 v[28:29], v[32:33], 1.0 op_sel_hi:[1,0]
	v_pk_add_f32 v[22:23], v[30:31], 1.0 op_sel_hi:[1,0]
	v_rcp_f32_e32 v28, v28
	v_rcp_f32_e32 v29, v29
	v_rcp_f32_e32 v22, v22
	v_rcp_f32_e32 v23, v23
	v_pk_mul_f32 v[24:25], v[34:35], v[28:29] op_sel_hi:[0,1]
	v_pk_mul_f32 v[18:19], v[24:25], v[18:19]
	s_nop 0
	v_cvt_pk_bf16_f32 v28, v18, v19
	v_pk_mul_f32 v[18:19], v[34:35], v[22:23] op_sel_hi:[0,1]
	v_pk_mul_f32 v[18:19], v[18:19], v[20:21]
	s_nop 0
	v_cvt_pk_bf16_f32 v29, v18, v19
	v_fmamk_f32 v18, v221, 0x3a800000, v220
	v_mul_f32_e32 v19, 0x4b800000, v18
	v_cmp_gt_f32_e32 vcc, s62, v18
	s_nop 1
	v_cndmask_b32_e32 v18, v18, v19, vcc
	v_rsq_f32_e32 v20, v18
	v_add_u32_e32 v18, 0xa0, v230
	v_mad_i64_i32 v[18:19], s[20:21], v18, s63, v[114:115]
	v_mul_f32_e32 v21, 0x45800000, v20
	v_cndmask_b32_e32 v21, v20, v21, vcc
	v_mul_f32_e32 v20, 0xbfb8aa3b, v21
	v_pk_mul_f32 v[22:23], v[20:21], v[14:15] op_sel_hi:[0,1]
	v_exp_f32_e32 v22, v22
	v_exp_f32_e32 v23, v23
	v_pk_mul_f32 v[14:15], v[20:21], v[16:17] op_sel_hi:[0,1]
	v_exp_f32_e32 v14, v14
	v_exp_f32_e32 v15, v15
	v_pk_add_f32 v[22:23], v[22:23], 1.0 op_sel_hi:[1,0]
	v_lshl_add_u64 v[18:19], v[18:19], 0, v[116:117]
	v_rcp_f32_e32 v22, v22
	v_rcp_f32_e32 v23, v23
	v_pk_add_f32 v[14:15], v[14:15], 1.0 op_sel_hi:[1,0]
	global_store_dwordx4 v[18:19], v[26:29], off
	v_rcp_f32_e32 v14, v14
	v_rcp_f32_e32 v15, v15
	v_mul_f32_e32 v18, v21, v21
	v_pk_mul_f32 v[16:17], v[18:19], v[22:23] op_sel_hi:[0,1]
	v_pk_mul_f32 v[10:11], v[16:17], v[10:11]
	v_pk_mul_f32 v[16:17], v[20:21], v[6:7] op_sel_hi:[0,1]
	v_exp_f32_e32 v16, v16
	v_exp_f32_e32 v17, v17
	v_pk_mul_f32 v[14:15], v[18:19], v[14:15] op_sel_hi:[0,1]
	v_pk_mul_f32 v[12:13], v[14:15], v[12:13]
	v_pk_mul_f32 v[14:15], v[20:21], v[8:9] op_sel_hi:[0,1]
	v_exp_f32_e32 v14, v14
	v_exp_f32_e32 v15, v15
	v_cvt_pk_bf16_f32 v10, v10, v11
	v_cvt_pk_bf16_f32 v11, v12, v13
	v_pk_add_f32 v[12:13], v[16:17], 1.0 op_sel_hi:[1,0]
	v_pk_add_f32 v[6:7], v[14:15], 1.0 op_sel_hi:[1,0]
	v_rcp_f32_e32 v12, v12
	v_rcp_f32_e32 v13, v13
	v_rcp_f32_e32 v6, v6
	v_rcp_f32_e32 v7, v7
	s_andn2_b64 vcc, exec, s[0:1]
	v_pk_mul_f32 v[8:9], v[18:19], v[12:13] op_sel_hi:[0,1]
	v_pk_mul_f32 v[2:3], v[8:9], v[2:3]
	s_mov_b64 s[0:1], -1
	v_cvt_pk_bf16_f32 v12, v2, v3
	v_pk_mul_f32 v[2:3], v[18:19], v[6:7] op_sel_hi:[0,1]
	v_pk_mul_f32 v[2:3], v[2:3], v[4:5]
	s_nop 0
	v_cvt_pk_bf16_f32 v13, v2, v3
	v_add_u32_e32 v2, 0xb0, v230
	v_mad_i64_i32 v[2:3], s[20:21], v2, s63, v[114:115]
	v_lshl_add_u64 v[2:3], v[2:3], 0, v[116:117]
	global_store_dwordx4 v[2:3], v[10:13], off
	s_cbranch_vccnz .LBB0_237
	s_andn2_b64 vcc, exec, s[6:7]
	s_cbranch_vccnz .LBB0_236
	s_barrier
	s_branch .LBB0_236
.LBB0_249:
	s_waitcnt vmcnt(0) lgkmcnt(0)
	s_barrier

; #define PG8_STAGE(bufoff, gbase, voff) do { _Pragma("unroll") for (int _i = 0; _i < 2; ++_i) \
;         __builtin_amdgcn_global_load_lds((const unsigned*)((const char*)(gbase) + (voff)[_i]), (LAS unsigned*)(lds + (bufoff) + ldsw + _i * 8192), 16, 0, 0); } while (0)
; #define PG8_WAIT_V(n) asm volatile("s_waitcnt vmcnt(" #n ")" ::: "memory")
; #define PG8_BAR __builtin_amdgcn_s_barrier()
; template <class Epi, class Sched>
; __device__ __forceinline__ void gemm_phase(LAS unsigned char* lds, const int lda, const int ldb, const int K, const Sched& S, const Epi& E) {
;     ...
;     for (int i = 0; i < 2; ++i) { int R, C; stage_rc(tid * 16 + i * 8192, R, C); const int Rb = (R & ~31) + perm32(R & 31);
;         voffA[i] = (unsigned)(R * lda + C) * 2u; voffB[i] = (unsigned)(Rb * ldb + C) * 2u; }
;     const size_t kstep = (size_t)(BK * 2);
;     const size_t hstepA = (size_t)HALF * lda * 2, hstepB = (size_t)HALF * ldb * 2;
;     const unsigned ldsw = (unsigned)wid * 1024u;
;     const int aoff = lds_byte(wr * 64 + fr, fq * 8), boff = lds_byte(wc * 32 + fr, fq * 8);
;     ...
;     Unit cur, nxt; int ui = 0;
;     if (!S.next(0, cur)) return;
;     f32x4 acc[2][2][4][2];
; #pragma unroll
;     for (int a = 0; a < 2; ++a)
; #pragma unroll
;         for (int b = 0; b < 2; ++b)
; #pragma unroll
;             for (int m = 0; m < 4; ++m)
; #pragma unroll
;                 for (int n = 0; n < 2; ++n) acc[a][b][m][n] = (f32x4){0.f, 0.f, 0.f, 0.f};
;     bf16x8 At[4][2], B0[2][2], B1[2][2];
;     float rsv[8];
; #pragma unroll
;     for (int i = 0; i < 8; ++i) rsv[i] = 0.f;
;     const char* cA = cur.A; const char* cB = cur.B;
;     PG8_STAGE(PG8_SB(0, 0), cB, voffB); PG8_STAGE(PG8_SB(0, 1), cB + hstepB, voffB); PG8_STAGE(PG8_SA(0, 0), cA, voffA); PG8_STAGE(PG8_SA(0, 1), cA + hstepA, voffA);
;     if (wr == 1) PG8_BAR;
;     PG8_WAIT_V(2); PG8_BAR;
;     PG8_STAGE(PG8_SB(1, 0), cB + kstep, voffB); PG8_STAGE(PG8_SA(1, 0), cA + kstep, voffA); PG8_STAGE(PG8_SB(1, 1), cB + hstepB + kstep, voffB);
;     PG8_WAIT_V(6); PG8_BAR;
.LBB0_1047:
	s_lshl_b32 s8, s8, 5
	s_and_b32 s14, s8, 0x60
	s_mov_b64 s[8:9], 0x80
	s_add_i32 m0, s39, 0x18000
	v_lshl_add_u64 v[8:9], v[8:9], 0, s[8:9]
	s_lshl_b32 s11, s10, 13
	s_lshl_b32 s15, s14, 7
	s_waitcnt vmcnt(2)
	s_barrier
	global_load_lds_dwordx4 v[8:9], off
	v_lshl_add_u64 v[6:7], v[6:7], 0, s[8:9]
	s_add_i32 m0, s39, 0x1a000
	s_add_i32 s44, s39, 0x8000
	s_add_i32 s45, s39, 0xa000
	global_load_lds_dwordx4 v[6:7], off
	v_lshl_add_u64 v[2:3], v[2:3], 0, s[8:9]
	s_mov_b32 m0, s44
	s_add_u32 s12, s24, 0x40080
	global_load_lds_dwordx4 v[2:3], off
	v_lshl_add_u64 v[2:3], v[4:5], 0, s[8:9]
	s_mov_b32 m0, s45
	s_addc_u32 s13, s25, 0
	global_load_lds_dwordx4 v[2:3], off
	s_add_i32 m0, s39, 0x1c000
	v_lshl_add_u64 v[2:3], s[12:13], 0, v[200:201]
	global_load_lds_dwordx4 v[2:3], off
	v_lshl_add_u64 v[2:3], s[12:13], 0, v[196:197]
	s_add_i32 m0, s39, 0x1e000
	s_sext_i32_i16 s64, s0
	global_load_lds_dwordx4 v[2:3], off
	v_and_b32_e32 v2, 15, v194
	v_lshlrev_b32_e32 v3, 1, v13
	v_lshl_or_b32 v1, s10, 6, v2
	v_lshl_or_b32 v4, v2, 6, v3
	v_lshlrev_b32_e32 v2, 2, v2
	v_and_b32_e32 v5, 32, v2
	v_bitop3_b32 v4, v4, s11, v5 bitop3:0xde
	v_lshlrev_b32_e32 v5, 6, v194
	s_movk_i32 s0, 0x3c0
	v_and_or_b32 v3, v5, s0, v3
	v_lshlrev_b32_e32 v5, 2, v194
	s_lshl_b32 s0, s10, 8
	v_and_b32_e32 v5, 32, v5
	s_add_u32 s10, s66, s0
	v_bitop3_b32 v195, s15, v3, v5 bitop3:0xf6
	s_addc_u32 s11, s67, 0
	v_mov_b32_e32 v3, v201
	v_lshl_add_u64 v[204:205], s[10:11], 0, v[2:3]
	v_lshlrev_b32_e32 v2, 8, v194
	v_and_b32_e32 v2, 0x38000, v2
	v_lshlrev_b32_e32 v3, 11, v14
	v_or3_b32 v2, v11, v2, v3
	v_add_u32_e32 v206, v2, v12
	v_lshlrev_b32_e32 v2, 4, v10
	s_waitcnt vmcnt(6)
	s_cmpk_lt_u32 s1, 0x100
	v_and_b32_e32 v2, 0x78000, v2
	s_cselect_b64 s[10:11], -1, 0
	v_or3_b32 v2, v11, v2, v3
	s_add_i32 s50, 0, 0x10000
	s_add_i32 s51, 0, 0x14000
	s_ashr_i32 s48, s58, 31
	s_mov_b32 s49, s58
	v_or_b32_e32 v216, s14, v13
	v_mov_b32_e32 v207, v201
	v_add_u32_e32 v208, v2, v12
	v_mov_b32_e32 v209, v201
	v_mov_b64_e32 v[210:211], 0x2100
	v_mov_b64_e32 v[212:213], 0x20ff
	v_add_u32_e32 v217, s50, v195
	v_add_u32_e32 v218, s51, v195
	v_add_u32_e32 v219, 0, v4
	v_mov_b32_e32 v220, 0x358637bd
	s_mov_b32 s62, 0x800000
	s_movk_i32 s63, 0x1600
	v_mov_b32_e32 v221, v201
	v_mov_b32_e32 v222, v201
	v_mov_b32_e32 v223, v201
	v_mov_b32_e32 v224, v201
	v_mov_b32_e32 v225, v201
	v_mov_b32_e32 v226, v201
	v_mov_b32_e32 v227, v201
	v_mov_b32_e32 v228, v201
	s_mov_b64 s[18:19], s[24:25]
	s_mov_b64 s[16:17], s[22:23]
	s_barrier
	ds_read_b128 v[130:133], v217
	ds_read_b128 v[134:137], v217 offset:1024
	ds_read_b128 v[138:141], v217 offset:2048
	ds_read_b128 v[142:145], v217 offset:3072
	ds_read_b128 v[146:149], v218
	ds_read_b128 v[150:153], v218 offset:1024
	ds_read_b128 v[154:157], v218 offset:2048
	ds_read_b128 v[158:161], v218 offset:3072
	ds_read_b128 v[162:165], v219
	ds_read_b128 v[166:169], v219 offset:1024
	ds_read_b128 v[170:173], v219 offset:2048
	ds_read_b128 v[174:177], v219 offset:3072
	ds_read_b128 v[178:181], v219 offset:4096
	ds_read_b128 v[182:185], v219 offset:5120
	ds_read_b128 v[186:189], v219 offset:6144
	ds_read_b128 v[190:193], v219 offset:7168
	s_branch .LBB0_1050

; #define PG8_STAGE(bufoff, gbase, voff) do { _Pragma("unroll") for (int _i = 0; _i < 2; ++_i) \
;         __builtin_amdgcn_global_load_lds((const unsigned*)((const char*)(gbase) + (voff)[_i]), (LAS unsigned*)(lds + (bufoff) + ldsw + _i * 8192), 16, 0, 0); } while (0)
; #define PG8_LDA(dst, b, h) do { _Pragma("unroll") for (int m = 0; m < 4; ++m) _Pragma("unroll") for (int k = 0; k < 2; ++k) dst[m][k] = *(const LAS bf16x8*)(lds + PG8_SA(b, h) + aoff + m * 2048 + k * 1024); } while (0)
; #define PG8_LDB(dst, b, h) do { _Pragma("unroll") for (int n = 0; n < 2; ++n) _Pragma("unroll") for (int k = 0; k < 2; ++k) dst[n][k] = *(const LAS bf16x8*)(lds + PG8_SB(b, h) + boff + n * 2048 + k * 1024); } while (0)
; #define PG8_MMA(ai, bj, At, Bt) do { __builtin_amdgcn_s_setprio(1); _Pragma("unroll") for (int m = 0; m < 4; ++m) _Pragma("unroll") for (int n = 0; n < 2; ++n) _Pragma("unroll") for (int k = 0; k < 2; ++k) \
;         acc[ai][bj][m][n] = __builtin_amdgcn_mfma_f32_16x16x32_bf16(Bt[n][k], At[m][k], acc[ai][bj][m][n], 0, 0, 0); __builtin_amdgcn_s_setprio(0); } while (0)
; #define PG8_WAIT_V(n) asm volatile("s_waitcnt vmcnt(" #n ")" ::: "memory")
; template <class Epi, class Sched>
; __device__ __forceinline__ void gemm_phase(LAS unsigned char* lds, const int lda, const int ldb, const int K, const Sched& S, const Epi& E) {
;     ...
;         const bool has_next = S.next(ui + 1, nxt);
;         const char* nA = has_next ? nxt.A : cA; const char* nB = has_next ? nxt.B : cB;
;         for (int t = 0; t < nt; t += 2) {
;             const bool last = (t == nt - 2);
;             const char* a1 = cA + (size_t)(t + 1) * kstep;
;             const char* a2 = last ? nA : cA + (size_t)(t + 2) * kstep; const char* b2 = last ? nB : cB + (size_t)(t + 2) * kstep;
;             const char* a3 = a2 + kstep; const char* b3 = b2 + kstep;
;             PG8_LDB(B0, 0, 0); PG8_LDB(B1, 0, 1); PG8_SCHED; PG8_LDA(At, 0, 0); PG8_STAGE(PG8_SA(1, 1), a1 + hstepA, voffA);
;             PG8_WAIT_V(8); PG8_WAIT_L(0); PG8_BAR; PG8_MMA(0, 0, At, B0); PG8_MMA(0, 1, At, B1); PG8_BAR; PG8_SCHED;
;             PG8_LDA(At, 0, 1); PG8_STAGE(PG8_SB(0, 0), b2, voffB); PG8_STAGE(PG8_SB(0, 1), b2 + hstepB, voffB); PG8_STAGE(PG8_SA(0, 0), a2, voffA);
;             PG8_WAIT_V(8); PG8_WAIT_L(0); PG8_BAR; PG8_MMA(1, 0, At, B0); PG8_MMA(1, 1, At, B1); PG8_BAR; PG8_SCHED;
.LBB0_1052:
	s_lshl_b32 s20, s20, 8
	s_ashr_i32 s21, s20, 31
	s_add_u32 s22, s22, 0x40080
	s_addc_u32 s23, s23, 0
	s_add_u32 s13, s24, 0x100
	v_lshl_add_u64 v[214:215], s[20:21], 2, v[204:205]
	s_addc_u32 s15, s25, 0
	s_mov_b32 s21, -2
	v_add_u32_e32 v230, 0x80, v200
	v_add_u32_e32 v231, 0x80, v196
	v_add_u32_e32 v232, 0x80, v202
	v_add_u32_e32 v233, 0x80, v198
	s_add_u32 s24, s22, 0xfffc0080
	s_addc_u32 s25, s23, -1
	s_cmp_eq_u32 s21, 12
	s_cselect_b32 s29, s17, s25
	s_cselect_b32 s28, s16, s24
	s_cselect_b32 s31, s19, s15
	s_cselect_b32 s30, s18, s13
	s_add_i32 s70, s50, s36
	s_add_i32 m0, s39, 0xc000
	s_add_i32 s69, s39, 0xe000
	s_add_i32 s71, s70, 0x2000
	s_add_u32 s34, s30, 0x40000
	s_addc_u32 s35, s31, 0
	s_add_i32 s72, s51, s36
	s_add_i32 s73, s72, 0x2000
	s_add_i32 s74, 0, 0x18000
	s_add_i32 s75, 0, 0x1c000
	s_add_u32 s26, s28, 0x40000
	s_addc_u32 s27, s29, 0
	s_add_i32 s66, s74, s36
	s_add_i32 s65, s66, 0x2000
	s_add_u32 s24, s30, 0x40080
	s_addc_u32 s25, s31, 0
	s_add_i32 s68, s75, s36
	s_add_i32 s67, s68, 0x2000
	s_cmp_lg_u32 s21, 12
	global_load_lds_dwordx4 v206, s[22:23]
	s_mov_b32 m0, s69
	s_nop 0
	global_load_lds_dwordx4 v208, s[22:23]
	s_waitcnt vmcnt(8)
	s_waitcnt lgkmcnt(0)
	s_barrier
	s_setprio 1
	s_waitcnt lgkmcnt(0)
	v_mfma_f32_16x16x32_bf16 v[126:129], v[130:133], v[162:165], 0
	v_mfma_f32_16x16x32_bf16 v[118:121], v[138:141], v[162:165], 0
	v_mfma_f32_16x16x32_bf16 v[110:113], v[130:133], v[170:173], 0
	v_mfma_f32_16x16x32_bf16 v[102:105], v[138:141], v[170:173], 0
	v_mfma_f32_16x16x32_bf16 v[94:97], v[130:133], v[178:181], 0
	v_mfma_f32_16x16x32_bf16 v[86:89], v[138:141], v[178:181], 0
	v_mfma_f32_16x16x32_bf16 v[78:81], v[130:133], v[186:189], 0
	v_mfma_f32_16x16x32_bf16 v[70:73], v[138:141], v[186:189], 0
	v_mfma_f32_16x16x32_bf16 v[126:129], v[134:137], v[166:169], v[126:129]
	v_mfma_f32_16x16x32_bf16 v[118:121], v[142:145], v[166:169], v[118:121]
	v_mfma_f32_16x16x32_bf16 v[110:113], v[134:137], v[174:177], v[110:113]
	v_mfma_f32_16x16x32_bf16 v[102:105], v[142:145], v[174:177], v[102:105]
	v_mfma_f32_16x16x32_bf16 v[94:97], v[134:137], v[182:185], v[94:97]
	v_mfma_f32_16x16x32_bf16 v[86:89], v[142:145], v[182:185], v[86:89]
	v_mfma_f32_16x16x32_bf16 v[78:81], v[134:137], v[190:193], v[78:81]
	v_mfma_f32_16x16x32_bf16 v[70:73], v[142:145], v[190:193], v[70:73]
	s_setprio 0
	s_setprio 1
	v_mfma_f32_16x16x32_bf16 v[122:125], v[146:149], v[162:165], 0
	v_mfma_f32_16x16x32_bf16 v[114:117], v[154:157], v[162:165], 0
	v_mfma_f32_16x16x32_bf16 v[106:109], v[146:149], v[170:173], 0
	v_mfma_f32_16x16x32_bf16 v[98:101], v[154:157], v[170:173], 0
	v_mfma_f32_16x16x32_bf16 v[90:93], v[146:149], v[178:181], 0
	v_mfma_f32_16x16x32_bf16 v[82:85], v[154:157], v[178:181], 0
	v_mfma_f32_16x16x32_bf16 v[74:77], v[146:149], v[186:189], 0
	v_mfma_f32_16x16x32_bf16 v[66:69], v[154:157], v[186:189], 0
	v_mfma_f32_16x16x32_bf16 v[122:125], v[150:153], v[166:169], v[122:125]
	v_mfma_f32_16x16x32_bf16 v[114:117], v[158:161], v[166:169], v[114:117]
	v_mfma_f32_16x16x32_bf16 v[106:109], v[150:153], v[174:177], v[106:109]
	v_mfma_f32_16x16x32_bf16 v[98:101], v[158:161], v[174:177], v[98:101]
	v_mfma_f32_16x16x32_bf16 v[90:93], v[150:153], v[182:185], v[90:93]
	v_mfma_f32_16x16x32_bf16 v[82:85], v[158:161], v[182:185], v[82:85]
	v_mfma_f32_16x16x32_bf16 v[74:77], v[150:153], v[190:193], v[74:77]
	v_mfma_f32_16x16x32_bf16 v[66:69], v[158:161], v[190:193], v[66:69]
	s_setprio 0
	s_barrier
	s_mov_b32 m0, s70
	ds_read_b128 v[162:165], v219 offset:16384
	ds_read_b128 v[166:169], v219 offset:17408
	ds_read_b128 v[170:173], v219 offset:18432
	ds_read_b128 v[174:177], v219 offset:19456
	ds_read_b128 v[178:181], v219 offset:20480
	ds_read_b128 v[182:185], v219 offset:21504
	ds_read_b128 v[186:189], v219 offset:22528
	ds_read_b128 v[190:193], v219 offset:23552
	global_load_lds_dwordx4 v200, s[30:31]
	s_mov_b32 m0, s71
	s_nop 0
	global_load_lds_dwordx4 v196, s[30:31]
	s_mov_b32 m0, s72
	s_nop 0
	global_load_lds_dwordx4 v200, s[34:35]
	s_mov_b32 m0, s73
	s_nop 0
	global_load_lds_dwordx4 v196, s[34:35]
	s_mov_b32 m0, s39
	s_nop 0
	global_load_lds_dwordx4 v202, s[28:29]
	s_mov_b32 m0, s40
	s_nop 0
	global_load_lds_dwordx4 v198, s[28:29]
	s_waitcnt vmcnt(8)
	s_waitcnt lgkmcnt(0)
	s_barrier
	s_setprio 1
	s_waitcnt lgkmcnt(0)
	v_mfma_f32_16x16x32_bf16 v[62:65], v[130:133], v[162:165], 0
	v_mfma_f32_16x16x32_bf16 v[54:57], v[138:141], v[162:165], 0
	v_mfma_f32_16x16x32_bf16 v[46:49], v[130:133], v[170:173], 0
	v_mfma_f32_16x16x32_bf16 v[38:41], v[138:141], v[170:173], 0
	v_mfma_f32_16x16x32_bf16 v[30:33], v[130:133], v[178:181], 0
	v_mfma_f32_16x16x32_bf16 v[22:25], v[138:141], v[178:181], 0
	v_mfma_f32_16x16x32_bf16 v[14:17], v[130:133], v[186:189], 0
	v_mfma_f32_16x16x32_bf16 v[6:9], v[138:141], v[186:189], 0
	v_mfma_f32_16x16x32_bf16 v[62:65], v[134:137], v[166:169], v[62:65]
	v_mfma_f32_16x16x32_bf16 v[54:57], v[142:145], v[166:169], v[54:57]
	v_mfma_f32_16x16x32_bf16 v[46:49], v[134:137], v[174:177], v[46:49]
	v_mfma_f32_16x16x32_bf16 v[38:41], v[142:145], v[174:177], v[38:41]
	v_mfma_f32_16x16x32_bf16 v[30:33], v[134:137], v[182:185], v[30:33]
	v_mfma_f32_16x16x32_bf16 v[22:25], v[142:145], v[182:185], v[22:25]
	v_mfma_f32_16x16x32_bf16 v[14:17], v[134:137], v[190:193], v[14:17]
	v_mfma_f32_16x16x32_bf16 v[6:9], v[142:145], v[190:193], v[6:9]
	s_setprio 0
	s_setprio 1
	v_mfma_f32_16x16x32_bf16 v[58:61], v[146:149], v[162:165], 0
	v_mfma_f32_16x16x32_bf16 v[50:53], v[154:157], v[162:165], 0
	v_mfma_f32_16x16x32_bf16 v[42:45], v[146:149], v[170:173], 0
	v_mfma_f32_16x16x32_bf16 v[34:37], v[154:157], v[170:173], 0
	v_mfma_f32_16x16x32_bf16 v[26:29], v[146:149], v[178:181], 0
	v_mfma_f32_16x16x32_bf16 v[18:21], v[154:157], v[178:181], 0
	v_mfma_f32_16x16x32_bf16 v[10:13], v[146:149], v[186:189], 0
	v_mfma_f32_16x16x32_bf16 v[2:5], v[154:157], v[186:189], 0
	v_mfma_f32_16x16x32_bf16 v[58:61], v[150:153], v[166:169], v[58:61]
	v_mfma_f32_16x16x32_bf16 v[50:53], v[158:161], v[166:169], v[50:53]
	v_mfma_f32_16x16x32_bf16 v[42:45], v[150:153], v[174:177], v[42:45]
	v_mfma_f32_16x16x32_bf16 v[34:37], v[158:161], v[174:177], v[34:37]
	v_mfma_f32_16x16x32_bf16 v[26:29], v[150:153], v[182:185], v[26:29]
	v_mfma_f32_16x16x32_bf16 v[18:21], v[158:161], v[182:185], v[18:21]
	v_mfma_f32_16x16x32_bf16 v[10:13], v[150:153], v[190:193], v[10:13]
	v_mfma_f32_16x16x32_bf16 v[2:5], v[158:161], v[190:193], v[2:5]
	s_setprio 0
	s_barrier
	s_branch .Lpeel6_join
